# nt only on the f32 row stores (XA / d_out) of the LN phases, bf16 HB stores left cached
# speedup vs baseline: 1.0017x; 1.0017x over previous
.LBB0_1053:
	s_or_b64 exec, exec, s[2:3]
	s_waitcnt vmcnt(0)
	v_add_f32_e32 v54, v34, v35
	v_add_f32_e32 v69, v36, v37
	v_add_f32_e32 v54, v54, v69
	v_add_f32_e32 v69, v38, v39
	v_add_f32_e32 v71, v40, v41
	v_add_f32_e32 v54, 0, v54
	v_add_f32_e32 v69, v69, v71
	v_add_f32_e32 v54, v54, v69
	v_add_f32_e32 v69, v42, v43
	v_add_f32_e32 v71, v44, v45
	v_mov_b32_e32 v78, v47
	v_mov_b32_e32 v79, v48
	v_mov_b32_e32 v80, v46
	v_mov_b32_e32 v81, v49
	v_add_f32_e32 v69, v69, v71
	v_pk_add_f32 v[78:79], v[78:79], v[80:81]
	v_add_f32_e32 v54, v54, v69
	v_add_f32_e32 v69, v78, v79
	v_add_f32_e32 v54, v54, v69
	v_cmp_gt_i32_e32 vcc, s20, v50
	v_mov_b32_e32 v77, v55
	v_add_f32_dpp v54, v54, v54 quad_perm:[1,0,3,2] row_mask:0xf bank_mask:0xf bound_ctrl:1
	v_mov_b32_e32 v73, v55
	v_lshl_add_u64 v[74:75], v[64:65], 0, v[74:75]
	v_add_f32_dpp v54, v54, v54 quad_perm:[2,3,0,1] row_mask:0xf bank_mask:0xf bound_ctrl:1
	s_nop 1
	v_add_f32_dpp v54, v54, v54 row_ror:4 row_mask:0xf bank_mask:0xf bound_ctrl:1
	s_nop 1
	v_add_f32_dpp v54, v54, v54 row_ror:8 row_mask:0xf bank_mask:0xf bound_ctrl:1
	ds_bpermute_b32 v69, v1, v54
	s_waitcnt lgkmcnt(0)
	v_add_f32_e32 v54, v54, v69
	ds_bpermute_b32 v69, v53, v54
	s_waitcnt lgkmcnt(0)
	v_add_f32_e32 v71, v54, v69
	v_cndmask_b32_e64 v54, v85, 0, vcc
	v_lshl_add_u64 v[78:79], s[58:59], 0, v[54:55]
	v_lshl_add_u64 v[106:107], v[78:79], 0, s[14:15]
	v_lshl_add_u64 v[102:103], v[78:79], 0, s[16:17]
	v_lshl_add_u64 v[78:79], v[106:107], 0, v[76:77]
	v_lshl_add_u64 v[80:81], v[102:103], 0, v[76:77]
	global_load_dwordx4 v[76:79], v[78:79], off
	s_nop 0
	global_load_dwordx4 v[80:83], v[80:81], off
	v_fmamk_f32 v35, v71, 0xba800000, v35
	v_fmamk_f32 v34, v71, 0xba800000, v34
	v_fmamk_f32 v37, v71, 0xba800000, v37
	v_fmac_f32_e32 v36, 0xba800000, v71
	v_pk_mul_f32 v[86:87], v[36:37], v[36:37]
	v_pk_mul_f32 v[88:89], v[34:35], v[34:35]
	v_fmamk_f32 v39, v71, 0xba800000, v39
	v_pk_mov_b32 v[90:91], v[88:89], v[86:87] op_sel:[1,0]
	v_mov_b32_e32 v89, v87
	v_pk_add_f32 v[86:87], v[90:91], v[88:89]
	v_fmamk_f32 v38, v71, 0xba800000, v38
	v_fmamk_f32 v41, v71, 0xba800000, v41
	v_fmac_f32_e32 v40, 0xba800000, v71
	v_pk_add_f32 v[94:95], v[86:87], v[86:87] op_sel_hi:[0,1]
	v_pk_mul_f32 v[86:87], v[40:41], v[40:41]
	v_pk_mul_f32 v[88:89], v[38:39], v[38:39]
	v_mov_b32_e32 v69, v55
	v_pk_mov_b32 v[90:91], v[88:89], v[86:87] op_sel:[1,0]
	v_mov_b32_e32 v89, v87
	v_pk_add_f32 v[86:87], v[90:91], v[88:89]
	v_lshl_add_u64 v[90:91], v[102:103], 0, v[68:69]
	v_pk_add_f32 v[96:97], v[86:87], v[86:87] op_sel_hi:[0,1]
	v_lshl_add_u64 v[86:87], v[106:107], 0, v[68:69]
	global_load_dwordx4 v[86:89], v[86:87], off
	s_nop 0
	global_load_dwordx4 v[90:93], v[90:91], off
	v_fmamk_f32 v42, v71, 0xba800000, v42
	v_fmamk_f32 v43, v71, 0xba800000, v43
	v_fmac_f32_e32 v44, 0xba800000, v71
	v_mul_f32_e32 v54, v42, v42
	v_fmamk_f32 v45, v71, 0xba800000, v45
	v_pk_fma_f32 v[98:99], v[42:43], v[42:43], v[54:55] op_sel_hi:[1,1,0]
	v_mul_f32_e32 v54, v44, v44
	v_pk_fma_f32 v[100:101], v[44:45], v[44:45], v[54:55] op_sel_hi:[1,1,0]
	v_fmamk_f32 v49, v71, 0xba800000, v49
	v_fmamk_f32 v48, v71, 0xba800000, v48
	v_fmamk_f32 v47, v71, 0xba800000, v47
	v_fmac_f32_e32 v46, 0xba800000, v71
	v_mul_f32_e32 v98, v46, v46
	v_mul_f32_e32 v100, v47, v47
	v_mul_f32_e32 v94, v48, v48
	v_mul_f32_e32 v96, v49, v49
	v_pk_add_f32 v[98:99], v[98:99], v[100:101]
	v_pk_add_f32 v[94:95], v[94:95], v[96:97]
	v_mov_b32_e32 v71, v55
	v_pk_add_f32 v[94:95], v[98:99], v[94:95]
	v_lshl_add_u64 v[98:99], v[102:103], 0, v[70:71]
	v_add_f32_e32 v54, v94, v95
	v_lshl_add_u64 v[94:95], v[106:107], 0, v[70:71]
	global_load_dwordx4 v[94:97], v[94:95], off
	s_nop 0
	global_load_dwordx4 v[98:101], v[98:99], off
	v_lshl_add_u64 v[102:103], v[102:103], 0, v[72:73]
	global_load_dwordx4 v[102:105], v[102:103], off
	v_lshl_add_u64 v[106:107], v[106:107], 0, v[72:73]
	global_load_dwordx4 v[106:109], v[106:107], off
	v_add_f32_dpp v54, v54, v54 quad_perm:[1,0,3,2] row_mask:0xf bank_mask:0xf bound_ctrl:1
	s_waitcnt vmcnt(6)
	v_pk_add_f32 v[80:81], v[80:81], 1.0 op_sel_hi:[1,0]
	v_add_f32_dpp v54, v54, v54 quad_perm:[2,3,0,1] row_mask:0xf bank_mask:0xf bound_ctrl:1
	v_pk_add_f32 v[82:83], v[82:83], 1.0 op_sel_hi:[1,0]
	s_nop 0
	v_add_f32_dpp v54, v54, v54 row_ror:4 row_mask:0xf bank_mask:0xf bound_ctrl:1
	s_nop 1
	v_add_f32_dpp v54, v54, v54 row_ror:8 row_mask:0xf bank_mask:0xf bound_ctrl:1
	ds_bpermute_b32 v69, v1, v54
	s_waitcnt lgkmcnt(0)
	v_add_f32_e32 v54, v54, v69
	ds_bpermute_b32 v69, v53, v54
	s_waitcnt lgkmcnt(0)
	v_add_f32_e32 v54, v54, v69
	v_fmamk_f32 v54, v54, 0x3a800000, v84
	v_mul_f32_e32 v69, 0x4b800000, v54
	v_cmp_gt_f32_e32 vcc, s21, v54
	s_nop 1
	v_cndmask_b32_e32 v54, v54, v69, vcc
	v_rsq_f32_e32 v54, v54
	s_nop 0
	v_mul_f32_e32 v69, 0x45800000, v54
	v_cndmask_b32_e32 v54, v54, v69, vcc
	v_pk_mul_f32 v[34:35], v[34:35], v[54:55] op_sel_hi:[1,0]
	v_pk_mul_f32 v[36:37], v[36:37], v[54:55] op_sel_hi:[1,0]
	v_pk_fma_f32 v[34:35], v[2:3], v[34:35], v[6:7]
	v_pk_fma_f32 v[36:37], v[4:5], v[36:37], v[8:9]
	global_store_dwordx4 v[74:75], v[34:37], off nt
	s_nop 1
	v_pk_fma_f32 v[34:35], v[80:81], v[34:35], v[76:77]
	v_pk_fma_f32 v[36:37], v[82:83], v[36:37], v[78:79]
	s_nop 0
	s_nop 0
	s_nop 0
	s_nop 0
	s_nop 0
	v_cvt_pk_bf16_f32 v34, v34, v35
	s_nop 0
	s_nop 0
	s_nop 0
	s_nop 0
	s_nop 0
	v_cvt_pk_bf16_f32 v35, v36, v37
	v_lshlrev_b64 v[36:37], 11, v[50:51]
	v_lshl_add_u64 v[76:77], v[66:67], 0, v[36:37]
	global_store_dwordx2 v[76:77], v[34:35], off
	v_pk_mul_f32 v[34:35], v[38:39], v[54:55] op_sel_hi:[1,0]
	v_pk_mul_f32 v[36:37], v[40:41], v[54:55] op_sel_hi:[1,0]
	v_pk_fma_f32 v[34:35], v[10:11], v[34:35], v[14:15]
	v_pk_fma_f32 v[36:37], v[12:13], v[36:37], v[16:17]
	s_waitcnt vmcnt(6)
	v_pk_add_f32 v[40:41], v[90:91], 1.0 op_sel_hi:[1,0]
	global_store_dwordx4 v[74:75], v[34:37], off offset:1024 nt
	v_pk_add_f32 v[38:39], v[92:93], 1.0 op_sel_hi:[1,0]
	v_add_u32_e32 v50, s13, v50
	v_pk_fma_f32 v[34:35], v[40:41], v[34:35], v[86:87]
	v_pk_fma_f32 v[36:37], v[38:39], v[36:37], v[88:89]
	s_nop 0
	s_nop 0
	s_nop 0
	s_nop 0
	s_nop 0
	v_cvt_pk_bf16_f32 v34, v34, v35
	s_nop 0
	s_nop 0
	s_nop 0
	s_nop 0
	s_nop 0
	v_cvt_pk_bf16_f32 v35, v36, v37
	global_store_dwordx2 v[76:77], v[34:35], off offset:512
	v_pk_mul_f32 v[34:35], v[42:43], v[54:55] op_sel_hi:[1,0]
	v_pk_mul_f32 v[36:37], v[44:45], v[54:55] op_sel_hi:[1,0]
	v_pk_fma_f32 v[34:35], v[18:19], v[34:35], v[22:23]
	v_pk_fma_f32 v[36:37], v[20:21], v[36:37], v[24:25]
	s_waitcnt vmcnt(6)
	v_pk_add_f32 v[40:41], v[98:99], 1.0 op_sel_hi:[1,0]
	global_store_dwordx4 v[74:75], v[34:37], off offset:2048 nt
	v_pk_add_f32 v[38:39], v[100:101], 1.0 op_sel_hi:[1,0]
	v_cmp_lt_i32_e32 vcc, s24, v50
	v_pk_fma_f32 v[34:35], v[40:41], v[34:35], v[94:95]
	v_pk_fma_f32 v[36:37], v[38:39], v[36:37], v[96:97]
	s_nop 0
	s_nop 0
	s_nop 0
	s_nop 0
	s_nop 0
	v_cvt_pk_bf16_f32 v34, v34, v35
	s_nop 0
	s_nop 0
	s_nop 0
	s_nop 0
	s_nop 0
	v_cvt_pk_bf16_f32 v35, v36, v37
	global_store_dwordx2 v[76:77], v[34:35], off offset:1024
	v_pk_mul_f32 v[34:35], v[46:47], v[54:55] op_sel_hi:[1,0]
	v_pk_mul_f32 v[36:37], v[48:49], v[54:55] op_sel_hi:[1,0]
	v_pk_fma_f32 v[34:35], v[26:27], v[34:35], v[30:31]
	v_pk_fma_f32 v[36:37], v[28:29], v[36:37], v[32:33]
	s_waitcnt vmcnt(7)
	v_pk_add_f32 v[40:41], v[102:103], 1.0 op_sel_hi:[1,0]
	global_store_dwordx4 v[74:75], v[34:37], off offset:3072 nt
	v_pk_add_f32 v[38:39], v[104:105], 1.0 op_sel_hi:[1,0]
	s_or_b64 s[10:11], vcc, s[10:11]
	s_waitcnt vmcnt(7)
	v_pk_fma_f32 v[34:35], v[40:41], v[34:35], v[106:107]
	v_pk_fma_f32 v[36:37], v[38:39], v[36:37], v[108:109]
	s_nop 0
	s_nop 0
	s_nop 0
	s_nop 0
	s_nop 0
	v_cvt_pk_bf16_f32 v34, v34, v35
	s_nop 0
	s_nop 0
	s_nop 0
	s_nop 0
	s_nop 0
	v_cvt_pk_bf16_f32 v35, v36, v37
	global_store_dwordx2 v[76:77], v[34:35], off offset:1536
	s_andn2_b64 exec, exec, s[10:11]
	s_cbranch_execz .LBB0_1070

.LBB0_1366:
	s_or_b64 exec, exec, s[2:3]
	s_waitcnt vmcnt(0)
	v_add_f32_e32 v54, v34, v35
	v_add_f32_e32 v69, v36, v37
	v_add_f32_e32 v54, v54, v69
	v_add_f32_e32 v69, v38, v39
	v_add_f32_e32 v71, v40, v41
	v_add_f32_e32 v54, 0, v54
	v_add_f32_e32 v69, v69, v71
	v_add_f32_e32 v54, v54, v69
	v_add_f32_e32 v69, v42, v43
	v_add_f32_e32 v71, v44, v45
	v_mov_b32_e32 v78, v47
	v_mov_b32_e32 v79, v48
	v_mov_b32_e32 v80, v46
	v_mov_b32_e32 v81, v49
	v_add_f32_e32 v69, v69, v71
	v_pk_add_f32 v[78:79], v[78:79], v[80:81]
	v_add_f32_e32 v54, v54, v69
	v_add_f32_e32 v69, v78, v79
	v_add_f32_e32 v54, v54, v69
	v_cmp_gt_i32_e32 vcc, s24, v50
	v_mov_b32_e32 v77, v55
	v_add_f32_dpp v54, v54, v54 quad_perm:[1,0,3,2] row_mask:0xf bank_mask:0xf bound_ctrl:1
	v_mov_b32_e32 v73, v55
	v_lshl_add_u64 v[74:75], v[64:65], 0, v[74:75]
	v_add_f32_dpp v54, v54, v54 quad_perm:[2,3,0,1] row_mask:0xf bank_mask:0xf bound_ctrl:1
	s_nop 1
	v_add_f32_dpp v54, v54, v54 row_ror:4 row_mask:0xf bank_mask:0xf bound_ctrl:1
	s_nop 1
	v_add_f32_dpp v54, v54, v54 row_ror:8 row_mask:0xf bank_mask:0xf bound_ctrl:1
	ds_bpermute_b32 v69, v1, v54
	s_waitcnt lgkmcnt(0)
	v_add_f32_e32 v54, v54, v69
	ds_bpermute_b32 v69, v53, v54
	s_waitcnt lgkmcnt(0)
	v_add_f32_e32 v71, v54, v69
	v_cndmask_b32_e64 v54, v85, 0, vcc
	v_lshl_add_u64 v[86:87], s[12:13], 0, v[54:55]
	v_lshl_add_u64 v[106:107], v[86:87], 0, s[16:17]
	v_lshl_add_u64 v[78:79], v[106:107], 0, v[76:77]
	global_load_dwordx4 v[78:81], v[78:79], off
	v_lshl_add_u64 v[76:77], v[86:87], 0, v[76:77]
	global_load_dwordx4 v[86:89], v[76:77], off
	v_fmamk_f32 v35, v71, 0xba800000, v35
	v_fmamk_f32 v34, v71, 0xba800000, v34
	v_fmamk_f32 v37, v71, 0xba800000, v37
	v_fmac_f32_e32 v36, 0xba800000, v71
	v_pk_mul_f32 v[82:83], v[36:37], v[36:37]
	v_pk_mul_f32 v[90:91], v[34:35], v[34:35]
	v_fmamk_f32 v39, v71, 0xba800000, v39
	v_pk_mov_b32 v[92:93], v[90:91], v[82:83] op_sel:[1,0]
	v_mov_b32_e32 v91, v83
	v_fmamk_f32 v38, v71, 0xba800000, v38
	v_fmamk_f32 v41, v71, 0xba800000, v41
	v_fmac_f32_e32 v40, 0xba800000, v71
	v_pk_add_f32 v[82:83], v[92:93], v[90:91]
	v_pk_mul_f32 v[90:91], v[40:41], v[40:41]
	v_pk_mul_f32 v[92:93], v[38:39], v[38:39]
	v_mov_b32_e32 v69, v55
	v_pk_mov_b32 v[94:95], v[92:93], v[90:91] op_sel:[1,0]
	v_mov_b32_e32 v93, v91
	v_pk_add_f32 v[90:91], v[94:95], v[92:93]
	global_load_dwordx4 v[94:97], v[76:77], off offset:1024
	v_pk_add_f32 v[98:99], v[90:91], v[90:91] op_sel_hi:[0,1]
	v_lshl_add_u64 v[90:91], v[106:107], 0, v[68:69]
	global_load_dwordx4 v[90:93], v[90:91], off
	v_fmamk_f32 v42, v71, 0xba800000, v42
	v_fmamk_f32 v43, v71, 0xba800000, v43
	v_fmac_f32_e32 v44, 0xba800000, v71
	v_mul_f32_e32 v54, v42, v42
	v_fmamk_f32 v45, v71, 0xba800000, v45
	v_pk_fma_f32 v[100:101], v[42:43], v[42:43], v[54:55] op_sel_hi:[1,1,0]
	v_mul_f32_e32 v54, v44, v44
	v_pk_add_f32 v[82:83], v[82:83], v[82:83] op_sel_hi:[0,1]
	v_pk_fma_f32 v[102:103], v[44:45], v[44:45], v[54:55] op_sel_hi:[1,1,0]
	v_fmamk_f32 v49, v71, 0xba800000, v49
	v_fmamk_f32 v48, v71, 0xba800000, v48
	v_fmamk_f32 v47, v71, 0xba800000, v47
	v_fmac_f32_e32 v46, 0xba800000, v71
	v_mul_f32_e32 v100, v46, v46
	v_mul_f32_e32 v102, v47, v47
	v_mul_f32_e32 v82, v48, v48
	v_mul_f32_e32 v98, v49, v49
	v_pk_add_f32 v[100:101], v[100:101], v[102:103]
	v_pk_add_f32 v[82:83], v[82:83], v[98:99]
	v_mov_b32_e32 v71, v55
	v_pk_add_f32 v[82:83], v[100:101], v[82:83]
	global_load_dwordx4 v[102:105], v[76:77], off offset:2048
	v_add_f32_e32 v54, v82, v83
	v_lshl_add_u64 v[82:83], v[106:107], 0, v[70:71]
	global_load_dwordx4 v[98:101], v[82:83], off
	v_lshl_add_u64 v[82:83], v[106:107], 0, v[72:73]
	global_load_dwordx4 v[106:109], v[82:83], off
	global_load_dwordx4 v[110:113], v[76:77], off offset:3072
	v_add_f32_dpp v54, v54, v54 quad_perm:[1,0,3,2] row_mask:0xf bank_mask:0xf bound_ctrl:1
	s_waitcnt vmcnt(7)
	v_pk_add_f32 v[78:79], v[78:79], 1.0 op_sel_hi:[1,0]
	v_add_f32_dpp v54, v54, v54 quad_perm:[2,3,0,1] row_mask:0xf bank_mask:0xf bound_ctrl:1
	v_pk_add_f32 v[76:77], v[80:81], 1.0 op_sel_hi:[1,0]
	s_nop 0
	v_add_f32_dpp v54, v54, v54 row_ror:4 row_mask:0xf bank_mask:0xf bound_ctrl:1
	s_nop 1
	v_add_f32_dpp v54, v54, v54 row_ror:8 row_mask:0xf bank_mask:0xf bound_ctrl:1
	ds_bpermute_b32 v69, v1, v54
	s_waitcnt lgkmcnt(0)
	v_add_f32_e32 v54, v54, v69
	ds_bpermute_b32 v69, v53, v54
	s_waitcnt lgkmcnt(0)
	v_add_f32_e32 v54, v54, v69
	v_fmamk_f32 v54, v54, 0x3a800000, v84
	v_mul_f32_e32 v69, 0x4b800000, v54
	v_cmp_gt_f32_e32 vcc, s25, v54
	s_nop 1
	v_cndmask_b32_e32 v54, v54, v69, vcc
	v_rsq_f32_e32 v54, v54
	s_nop 0
	v_mul_f32_e32 v69, 0x45800000, v54
	v_cndmask_b32_e32 v54, v54, v69, vcc
	v_pk_mul_f32 v[34:35], v[34:35], v[54:55] op_sel_hi:[1,0]
	v_pk_mul_f32 v[36:37], v[36:37], v[54:55] op_sel_hi:[1,0]
	v_pk_fma_f32 v[34:35], v[2:3], v[34:35], v[6:7]
	v_pk_fma_f32 v[36:37], v[4:5], v[36:37], v[8:9]
	global_store_dwordx4 v[74:75], v[34:37], off nt
	s_waitcnt vmcnt(7)
	s_nop 0
	v_pk_fma_f32 v[34:35], v[78:79], v[34:35], v[86:87]
	v_pk_fma_f32 v[36:37], v[76:77], v[36:37], v[88:89]
	s_nop 0
	s_nop 0
	s_nop 0
	s_nop 0
	s_nop 0
	v_cvt_pk_bf16_f32 v34, v34, v35
	s_nop 0
	s_nop 0
	s_nop 0
	s_nop 0
	s_nop 0
	v_cvt_pk_bf16_f32 v35, v36, v37
	v_lshlrev_b64 v[36:37], 11, v[50:51]
	v_lshl_add_u64 v[76:77], v[66:67], 0, v[36:37]
	global_store_dwordx2 v[76:77], v[34:35], off
	v_pk_mul_f32 v[34:35], v[38:39], v[54:55] op_sel_hi:[1,0]
	v_pk_mul_f32 v[36:37], v[40:41], v[54:55] op_sel_hi:[1,0]
	v_pk_fma_f32 v[34:35], v[10:11], v[34:35], v[14:15]
	v_pk_fma_f32 v[36:37], v[12:13], v[36:37], v[16:17]
	s_waitcnt vmcnt(6)
	v_pk_add_f32 v[40:41], v[90:91], 1.0 op_sel_hi:[1,0]
	global_store_dwordx4 v[74:75], v[34:37], off offset:1024 nt
	v_pk_add_f32 v[38:39], v[92:93], 1.0 op_sel_hi:[1,0]
	v_add_u32_e32 v50, s21, v50
	v_pk_fma_f32 v[34:35], v[40:41], v[34:35], v[94:95]
	v_pk_fma_f32 v[36:37], v[38:39], v[36:37], v[96:97]
	s_nop 0
	s_nop 0
	s_nop 0
	s_nop 0
	s_nop 0
	v_cvt_pk_bf16_f32 v34, v34, v35
	s_nop 0
	s_nop 0
	s_nop 0
	s_nop 0
	s_nop 0
	v_cvt_pk_bf16_f32 v35, v36, v37
	global_store_dwordx2 v[76:77], v[34:35], off offset:512
	v_pk_mul_f32 v[34:35], v[42:43], v[54:55] op_sel_hi:[1,0]
	v_pk_mul_f32 v[36:37], v[44:45], v[54:55] op_sel_hi:[1,0]
	v_pk_fma_f32 v[34:35], v[18:19], v[34:35], v[22:23]
	v_pk_fma_f32 v[36:37], v[20:21], v[36:37], v[24:25]
	s_waitcnt vmcnt(6)
	v_pk_add_f32 v[40:41], v[98:99], 1.0 op_sel_hi:[1,0]
	global_store_dwordx4 v[74:75], v[34:37], off offset:2048 nt
	v_pk_add_f32 v[38:39], v[100:101], 1.0 op_sel_hi:[1,0]
	v_cmp_lt_i32_e32 vcc, s28, v50
	v_pk_fma_f32 v[34:35], v[40:41], v[34:35], v[102:103]
	v_pk_fma_f32 v[36:37], v[38:39], v[36:37], v[104:105]
	s_nop 0
	s_nop 0
	s_nop 0
	s_nop 0
	s_nop 0
	v_cvt_pk_bf16_f32 v34, v34, v35
	s_nop 0
	s_nop 0
	s_nop 0
	s_nop 0
	s_nop 0
	v_cvt_pk_bf16_f32 v35, v36, v37
	global_store_dwordx2 v[76:77], v[34:35], off offset:1024
	v_pk_mul_f32 v[34:35], v[46:47], v[54:55] op_sel_hi:[1,0]
	v_pk_mul_f32 v[36:37], v[48:49], v[54:55] op_sel_hi:[1,0]
	v_pk_fma_f32 v[34:35], v[26:27], v[34:35], v[30:31]
	v_pk_fma_f32 v[36:37], v[28:29], v[36:37], v[32:33]
	s_waitcnt vmcnt(7)
	v_pk_add_f32 v[40:41], v[106:107], 1.0 op_sel_hi:[1,0]
	global_store_dwordx4 v[74:75], v[34:37], off offset:3072 nt
	v_pk_add_f32 v[38:39], v[108:109], 1.0 op_sel_hi:[1,0]
	s_or_b64 s[18:19], vcc, s[18:19]
	s_waitcnt vmcnt(7)
	v_pk_fma_f32 v[34:35], v[40:41], v[34:35], v[110:111]
	v_pk_fma_f32 v[36:37], v[38:39], v[36:37], v[112:113]
	s_nop 0
	s_nop 0
	s_nop 0
	s_nop 0
	s_nop 0
	v_cvt_pk_bf16_f32 v34, v34, v35
	s_nop 0
	s_nop 0
	s_nop 0
	s_nop 0
	s_nop 0
	v_cvt_pk_bf16_f32 v35, v36, v37
	global_store_dwordx2 v[76:77], v[34:35], off offset:1536
	s_andn2_b64 exec, exec, s[18:19]
	s_cbranch_execz .LBB0_1383

.LBB0_1847:
	v_ashrrev_i32_e32 v55, 31, v54
	v_lshlrev_b64 v[92:93], 12, v[54:55]
	v_lshl_add_u64 v[94:95], v[56:57], 0, v[92:93]
	global_load_dwordx4 v[80:83], v[94:95], off
	global_load_dwordx4 v[84:87], v[94:95], off offset:1024
	global_load_dwordx4 v[88:91], v[94:95], off offset:2048
	global_load_dwordx4 v[50:53], v[94:95], off offset:3072
	v_lshl_add_u64 v[92:93], v[58:59], 0, v[92:93]
	s_waitcnt vmcnt(3)
	v_mov_b32_e32 v94, v81
	v_mov_b32_e32 v95, v82
	v_mov_b32_e32 v96, v80
	v_mov_b32_e32 v97, v83
	s_waitcnt vmcnt(2)
	v_mov_b32_e32 v98, v85
	v_mov_b32_e32 v99, v86
	v_mov_b32_e32 v100, v84
	v_mov_b32_e32 v101, v87
	v_pk_add_f32 v[94:95], v[94:95], v[96:97]
	v_pk_add_f32 v[96:97], v[98:99], v[100:101]
	v_add_f32_e32 v100, v94, v95
	v_pk_add_f32 v[94:95], v[96:97], v[96:97] op_sel:[0,1] op_sel_hi:[1,0]
	s_waitcnt vmcnt(1)
	v_add_f32_e32 v102, v88, v89
	v_add_f32_e32 v104, v90, v91
	s_waitcnt vmcnt(0)
	v_mov_b32_e32 v107, v50
	v_mov_b32_e32 v103, v52
	v_mov_b32_e32 v105, v53
	v_add_f32_e32 v106, 0, v100
	v_mov_b32_e32 v95, v51
	v_pk_add_f32 v[98:99], v[102:103], v[104:105]
	v_pk_add_f32 v[94:95], v[106:107], v[94:95]
	s_nop 0
	v_pk_add_f32 v[94:95], v[94:95], v[98:99]
	s_nop 0
	v_add_f32_e32 v94, v94, v95
	s_nop 1
	v_add_f32_dpp v94, v94, v94 quad_perm:[1,0,3,2] row_mask:0xf bank_mask:0xf bound_ctrl:1
	s_nop 1
	v_add_f32_dpp v94, v94, v94 quad_perm:[2,3,0,1] row_mask:0xf bank_mask:0xf bound_ctrl:1
	s_nop 1
	v_add_f32_dpp v94, v94, v94 row_ror:4 row_mask:0xf bank_mask:0xf bound_ctrl:1
	s_nop 1
	v_add_f32_dpp v94, v94, v94 row_ror:8 row_mask:0xf bank_mask:0xf bound_ctrl:1
	ds_bpermute_b32 v95, v78, v94
	s_waitcnt lgkmcnt(0)
	v_add_f32_e32 v94, v94, v95
	ds_bpermute_b32 v95, v79, v94
	s_waitcnt lgkmcnt(0)
	v_add_f32_e32 v94, v94, v95
	v_fmamk_f32 v81, v94, 0xba800000, v81
	v_fmamk_f32 v80, v94, 0xba800000, v80
	v_fmamk_f32 v83, v94, 0xba800000, v83
	v_fmac_f32_e32 v82, 0xba800000, v94
	v_fmamk_f32 v85, v94, 0xba800000, v85
	v_fmamk_f32 v84, v94, 0xba800000, v84
	v_fmamk_f32 v87, v94, 0xba800000, v87
	v_fmac_f32_e32 v86, 0xba800000, v94
	v_fmamk_f32 v89, v94, 0xba800000, v89
	v_fmamk_f32 v88, v94, 0xba800000, v88
	v_fmamk_f32 v91, v94, 0xba800000, v91
	v_fmac_f32_e32 v90, 0xba800000, v94
	v_fmamk_f32 v53, v94, 0xba800000, v53
	v_fmamk_f32 v52, v94, 0xba800000, v52
	v_fmamk_f32 v51, v94, 0xba800000, v51
	v_fmac_f32_e32 v50, 0xba800000, v94
	v_pk_mul_f32 v[94:95], v[82:83], v[82:83]
	v_pk_mul_f32 v[96:97], v[80:81], v[80:81]
	v_pk_mul_f32 v[98:99], v[86:87], v[86:87]
	v_pk_mul_f32 v[100:101], v[84:85], v[84:85]
	v_pk_mov_b32 v[106:107], v[96:97], v[94:95] op_sel:[1,0]
	v_mov_b32_e32 v97, v95
	v_pk_mov_b32 v[94:95], v[100:101], v[98:99] op_sel:[1,0]
	v_mov_b32_e32 v101, v99
	v_mul_f32_e32 v102, v88, v88
	v_mul_f32_e32 v104, v90, v90
	v_pk_add_f32 v[96:97], v[106:107], v[96:97]
	v_pk_add_f32 v[94:95], v[94:95], v[100:101]
	v_pk_fma_f32 v[98:99], v[88:89], v[88:89], v[102:103] op_sel_hi:[1,1,0]
	v_pk_fma_f32 v[102:103], v[90:91], v[90:91], v[104:105] op_sel_hi:[1,1,0]
	v_pk_add_f32 v[96:97], v[96:97], v[96:97] op_sel_hi:[0,1]
	v_pk_add_f32 v[94:95], v[94:95], v[94:95] op_sel_hi:[0,1]
	v_mul_f32_e32 v98, v50, v50
	v_mul_f32_e32 v102, v51, v51
	v_mul_f32_e32 v96, v52, v52
	v_mul_f32_e32 v94, v53, v53
	v_pk_add_f32 v[98:99], v[98:99], v[102:103]
	v_pk_add_f32 v[94:95], v[96:97], v[94:95]
	s_nop 0
	v_pk_add_f32 v[94:95], v[98:99], v[94:95]
	s_nop 0
	v_add_f32_e32 v94, v94, v95
	s_nop 1
	v_add_f32_dpp v94, v94, v94 quad_perm:[1,0,3,2] row_mask:0xf bank_mask:0xf bound_ctrl:1
	s_nop 1
	v_add_f32_dpp v94, v94, v94 quad_perm:[2,3,0,1] row_mask:0xf bank_mask:0xf bound_ctrl:1
	s_nop 1
	v_add_f32_dpp v94, v94, v94 row_ror:4 row_mask:0xf bank_mask:0xf bound_ctrl:1
	s_nop 1
	v_add_f32_dpp v94, v94, v94 row_ror:8 row_mask:0xf bank_mask:0xf bound_ctrl:1
	ds_bpermute_b32 v95, v78, v94
	s_waitcnt lgkmcnt(0)
	v_add_f32_e32 v94, v94, v95
	ds_bpermute_b32 v95, v79, v94
	s_waitcnt lgkmcnt(0)
	v_add_f32_e32 v94, v94, v95
	v_fmamk_f32 v94, v94, 0x3a800000, v1
	v_mul_f32_e32 v95, 0x4b800000, v94
	v_cmp_gt_f32_e32 vcc, s11, v94
	s_nop 1
	v_cndmask_b32_e32 v94, v94, v95, vcc
	v_rsq_f32_e32 v96, v94
	v_lshlrev_b64 v[94:95], 11, v[54:55]
	v_lshl_add_u64 v[94:95], v[60:61], 0, v[94:95]
	v_add_u32_e32 v54, s10, v54
	v_mul_f32_e32 v55, 0x45800000, v96
	v_cndmask_b32_e32 v96, v96, v55, vcc
	v_pk_mul_f32 v[80:81], v[80:81], v[96:97] op_sel_hi:[1,0]
	v_pk_mul_f32 v[82:83], v[82:83], v[96:97] op_sel_hi:[1,0]
	v_pk_mul_f32 v[84:85], v[84:85], v[96:97] op_sel_hi:[1,0]
	v_pk_mul_f32 v[86:87], v[86:87], v[96:97] op_sel_hi:[1,0]
	v_pk_fma_f32 v[82:83], v[4:5], v[82:83], v[8:9]
	v_pk_fma_f32 v[80:81], v[2:3], v[80:81], v[6:7]
	v_pk_fma_f32 v[86:87], v[12:13], v[86:87], v[16:17]
	v_pk_fma_f32 v[84:85], v[10:11], v[84:85], v[14:15]
	global_store_dwordx4 v[92:93], v[80:83], off nt
	v_pk_mul_f32 v[88:89], v[88:89], v[96:97] op_sel_hi:[1,0]
	v_pk_mul_f32 v[90:91], v[90:91], v[96:97] op_sel_hi:[1,0]
	v_pk_fma_f32 v[82:83], v[62:63], v[82:83], v[20:21]
	v_pk_fma_f32 v[80:81], v[64:65], v[80:81], v[18:19]
	global_store_dwordx4 v[92:93], v[84:87], off offset:1024 nt
	v_bfe_u32 v55, v80, 16, 1
	v_bfe_u32 v97, v81, 16, 1
	v_pk_fma_f32 v[86:87], v[66:67], v[86:87], v[24:25]
	v_pk_fma_f32 v[84:85], v[68:69], v[84:85], v[22:23]
	v_bfe_u32 v98, v82, 16, 1
	v_pk_fma_f32 v[90:91], v[36:37], v[90:91], v[40:41]
	v_pk_fma_f32 v[88:89], v[34:35], v[88:89], v[38:39]
	v_bfe_u32 v99, v83, 16, 1
	v_bfe_u32 v100, v84, 16, 1
	v_bfe_u32 v101, v85, 16, 1
	s_nop 0
	v_add3_u32 v55, v80, v55, s12
	v_add3_u32 v80, v81, v97, s12
	v_add3_u32 v81, v82, v98, s12
	global_store_dwordx4 v[92:93], v[88:91], off offset:2048 nt
	s_nop 0
	v_add3_u32 v82, v83, v99, s12
	v_pk_fma_f32 v[90:91], v[70:71], v[90:91], v[28:29]
	v_add3_u32 v83, v84, v100, s12
	v_add3_u32 v84, v85, v101, s12
	s_nop 0
	v_lshrrev_b32_e32 v55, 16, v55
	v_lshrrev_b32_e32 v81, 16, v81
	s_nop 0
	v_lshrrev_b32_e32 v83, 16, v83
	s_nop 0
	v_and_or_b32 v80, v80, s13, v55
	v_and_or_b32 v81, v82, s13, v81
	s_nop 0
	v_pk_mul_f32 v[50:51], v[50:51], v[96:97] op_sel_hi:[1,0]
	v_pk_mul_f32 v[52:53], v[52:53], v[96:97] op_sel_hi:[1,0]
	v_and_or_b32 v82, v84, s13, v83
	v_cvt_pk_bf16_f32 v83, v86, v87
	global_store_dwordx2 v[94:95], v[80:81], off
	global_store_dwordx2 v[94:95], v[82:83], off offset:512
	s_nop 0
	s_nop 0
	v_pk_fma_f32 v[52:53], v[44:45], v[52:53], v[48:49]
	v_pk_fma_f32 v[50:51], v[42:43], v[50:51], v[46:47]
	s_nop 0
	s_nop 0
	global_store_dwordx4 v[92:93], v[50:53], off offset:3072 nt
	v_cvt_pk_bf16_f32 v81, v90, v91
	v_pk_fma_f32 v[88:89], v[72:73], v[88:89], v[26:27]
	v_pk_fma_f32 v[50:51], v[76:77], v[50:51], v[30:31]
	v_pk_fma_f32 v[52:53], v[74:75], v[52:53], v[32:33]
	s_nop 0
	s_nop 0
	s_nop 0
	s_nop 0
	s_nop 0
	s_nop 0
	v_cvt_pk_bf16_f32 v50, v50, v51
	s_nop 0
	s_nop 0
	s_nop 0
	s_nop 0
	s_nop 0
	s_nop 0
	s_nop 0
	s_nop 0
	s_nop 0
	v_cmp_lt_i32_e32 vcc, s14, v54
	v_cvt_pk_bf16_f32 v80, v88, v89
	v_cvt_pk_bf16_f32 v51, v52, v53
	s_or_b64 s[4:5], vcc, s[4:5]
	global_store_dwordx2 v[94:95], v[80:81], off offset:1024
	global_store_dwordx2 v[94:95], v[50:51], off offset:1536
	s_andn2_b64 exec, exec, s[4:5]
	s_cbranch_execnz .LBB0_1847
